# phase C: window block list via v_readlane; chunk K/V fragment ds_reads issued right after the barrier
# baseline (speedup 1.0000x reference)
; DI void nsa_ldsfrag(KVFrag& f, const unsigned char* slot, int qi, int quad) {
;     ...
;   for (int a = 0; a < 2; ++a) { const unsigned char* kp = slot + (krow + 4 * a) * NSA_KROW + quad * 16; f.k[a][0] = mk8(*(const u32x4*)kp); f.k[a][1] = mk8(*(const u32x4*)(kp + 64)); }
; #pragma unroll
;   for (int dt = 0; dt < 4; ++dt) f.v[dt] = mk8(*(const u32x4*)(slot + 32 * NSA_KROW + (dt * 16 + qi) * NSA_VROW + quad * 16));
; template <int MODE>
; DI void nsa_branch(const bf16_t* __restrict__ Kb, const bf16_t* __restrict__ Vtb, unsigned char* lds, int nb, int t, int cur, unsigned selmask, unsigned umall,
;                    const bf16x8 (&qf)[4][2], f32x4 (&O)[4][4], float (&m)[4], float (&l)[4], bool online) {
;     ...
;   for (int n = 0; n < N; n += 2) {
;     const int j = blist[n >> 1];
;     const bool won = MODE == 0 ? ((umall >> j) & 1u) != 0 : (j >= cur - 8 && j <= cur);
;     const bool bit = (selmask >> j) & 1u;
;     ra = *(const u32x4*)(gsrc + (long)kbof(min(n + 2, N - 2)) * gmul);
;     if (won) { KVFrag f; nsa_ldsfrag(f, slot0, qi, quad); nsa_chunk<MODE>(f, j * 64, t, bit, qf, O, m, l, quad, online); }
.LBB0_727:
	ds_read_b128 v[136:139], v176
	ds_read_b128 v[140:143], v176 offset:64
	ds_read_b128 v[144:147], v176 offset:576
	ds_read_b128 v[132:135], v176 offset:640
	ds_read_b128 v[128:131], v177
	ds_read_b128 v[124:127], v177 offset:1280
	ds_read_b128 v[120:123], v177 offset:2560
	s_sub_u32 s58, s56, 0x14c20
	s_lshr_b32 s58, s58, 2
	v_readlane_b32 s0, v216, s58
	s_nop 1
	v_mov_b32_e32 v181, s0
	s_lshl_b32 s10, 1, s0
	s_and_b32 s11, s10, s42
	s_cmp_lg_u32 s11, 0
	s_cselect_b64 s[0:1], -1, 0
	s_add_i32 s57, s54, -1
	s_min_i32 s12, s57, s43
	s_lshr_b32 s12, s12, 1
	v_readlane_b32 s58, v216, s12
	v_and_b32_e32 v116, s10, v171
	v_cmp_ne_u32_e64 s[12:13], 0, v116
	v_cndmask_b32_e64 v116, 0, 1, s[8:9]
	s_lshl_b32 s58, s58, 6
	s_ashr_i32 s59, s58, 31
	s_lshl_b64 s[58:59], s[58:59], 7
	s_cmp_eq_u32 s11, 0
	v_lshl_add_u64 v[112:113], v[168:169], 0, s[58:59]
	global_load_dwordx4 v[112:115], v[112:113], off
	v_cmp_ne_u32_e64 s[10:11], 1, v116
	s_cbranch_scc1 .LBB0_737
	s_and_b64 vcc, exec, s[10:11]
	s_cbranch_vccz .Lmy_nf_s1
	v_readfirstlane_b32 s58, v181
	v_readfirstlane_b32 s59, v160
	s_lshl_b32 s58, s58, 6
	s_add_u32 s60, s58, 63
	s_cmp_le_i32 s60, s59
	s_cbranch_scc0 .Lmy_nf_s1
	ds_read_b128 v[116:119], v177 offset:3840
	v_mov_b32_e32 v226, 0xff800000
	v_cndmask_b32_e64 v218, v226, 0, s[12:13]
	v_cndmask_b32_e64 v219, v226, 0, s[12:13]
	v_cndmask_b32_e64 v220, v226, 0, s[12:13]
	v_cndmask_b32_e64 v221, v226, 0, s[12:13]
	s_branch .Lmy_full_s1
.Lmy_nf_s1:
	v_lshl_or_b32 v182, v181, 6, v173
	v_cmp_le_i32_e32 vcc, v182, v160
	s_and_b64 s[16:17], s[12:13], vcc
	v_cmp_lt_i32_e32 vcc, v182, v160
	v_or_b32_e32 v148, 2, v182
	s_and_b64 s[18:19], s[12:13], vcc
	v_cmp_le_i32_e32 vcc, v148, v160
	v_or_b32_e32 v148, 3, v182
	s_and_b64 s[44:45], s[12:13], vcc
	v_cmp_le_i32_e32 vcc, v148, v160
	v_or_b32_e32 v148, 4, v182
	ds_read_b128 v[116:119], v177 offset:3840
	s_and_b64 s[46:47], s[12:13], vcc
	v_cmp_le_i32_e32 vcc, v148, v160
	v_or_b32_e32 v152, 5, v182
	s_and_b64 s[14:15], s[12:13], vcc
	v_cmp_le_i32_e32 vcc, v152, v160
	v_or_b32_e32 v183, 6, v182
	s_and_b64 s[48:49], s[12:13], vcc
	v_cmp_le_i32_e32 vcc, v183, v160
	v_or_b32_e32 v182, 7, v182
	s_and_b64 s[50:51], s[12:13], vcc
	v_cmp_le_i32_e32 vcc, v182, v160
	s_and_b64 s[52:53], s[12:13], vcc
	s_and_b64 vcc, exec, s[10:11]
	v_mov_b32_e32 v226, 0xff800000
	v_cndmask_b32_e64 v218, v226, 0, s[16:17]
	v_cndmask_b32_e64 v219, v226, 0, s[18:19]
	v_cndmask_b32_e64 v220, v226, 0, s[44:45]
	v_cndmask_b32_e64 v221, v226, 0, s[46:47]
	v_cndmask_b32_e64 v222, v226, 0, s[14:15]
	v_cndmask_b32_e64 v223, v226, 0, s[48:49]
	v_cndmask_b32_e64 v224, v226, 0, s[50:51]
	v_cndmask_b32_e64 v225, v226, 0, s[52:53]
	s_nop 1
	s_cbranch_vccnz .Lmy_fast_s1
	s_waitcnt lgkmcnt(7)
	v_mfma_f32_16x16x32_bf16 v[148:151], v[136:139], v[8:11], v[218:221]
	s_waitcnt lgkmcnt(6)
	v_mfma_f32_16x16x32_bf16 v[152:155], v[140:143], v[12:15], v[148:151]
	s_waitcnt lgkmcnt(5)
	v_mfma_f32_16x16x32_bf16 v[148:151], v[144:147], v[8:11], v[222:225]
	s_waitcnt lgkmcnt(4)
	v_mfma_f32_16x16x32_bf16 v[148:151], v[132:135], v[12:15], v[148:151]
	s_nop 7
	s_cbranch_vccnz .LBB0_730
	v_mul_f32_e32 v182, 0x3e38aa3b, v152
	v_max_f32_e32 v182, 0xf149f2ca, v182
	v_cndmask_b32_e64 v182, v232, v182, s[16:17]
	v_mul_f32_e32 v183, 0x3e38aa3b, v153
	v_max_f32_e32 v183, v182, v183
	v_cndmask_b32_e64 v182, v182, v183, s[18:19]
	v_mul_f32_e32 v183, 0x3e38aa3b, v154
	v_max_f32_e32 v183, v182, v183
	v_cndmask_b32_e64 v182, v182, v183, s[44:45]
	v_mul_f32_e32 v183, 0x3e38aa3b, v155
	v_max_f32_e32 v183, v182, v183
	v_cndmask_b32_e64 v182, v182, v183, s[46:47]
	v_mul_f32_e32 v183, 0x3e38aa3b, v148
	v_max_f32_e32 v183, v182, v183
	v_cndmask_b32_e64 v182, v182, v183, s[14:15]
	v_mul_f32_e32 v183, 0x3e38aa3b, v149
	v_max_f32_e32 v184, v182, v182
	v_max_f32_e32 v183, v184, v183
	v_cndmask_b32_e64 v182, v182, v183, s[48:49]
	v_mul_f32_e32 v183, 0x3e38aa3b, v150
	v_max_f32_e32 v184, v182, v182
	v_max_f32_e32 v183, v184, v183
	v_cndmask_b32_e64 v182, v182, v183, s[50:51]
	v_mul_f32_e32 v183, 0x3e38aa3b, v151
	v_max_f32_e32 v184, v182, v182
	v_max_f32_e32 v183, v184, v183
	v_cndmask_b32_e64 v182, v182, v183, s[52:53]
	ds_bpermute_b32 v183, v175, v182
	v_max_f32_e32 v182, v182, v182
	s_waitcnt lgkmcnt(0)
	v_max_f32_e32 v183, v183, v183
	v_max_f32_e32 v182, v182, v183
	ds_bpermute_b32 v183, v159, v182
	s_waitcnt lgkmcnt(0)
	v_max3_f32 v183, v3, v182, v183
	v_sub_f32_e32 v3, v3, v183
	v_exp_f32_e32 v182, v3
	v_mov_b32_e32 v3, v183
	v_mul_f32_e32 v167, v167, v182
	v_pk_mul_f32 v[106:107], v[106:107], v[182:183] op_sel_hi:[1,0]
	v_pk_mul_f32 v[104:105], v[104:105], v[182:183] op_sel_hi:[1,0]
	v_pk_mul_f32 v[102:103], v[102:103], v[182:183] op_sel_hi:[1,0]
	v_pk_mul_f32 v[100:101], v[100:101], v[182:183] op_sel_hi:[1,0]
	v_pk_mul_f32 v[98:99], v[98:99], v[182:183] op_sel_hi:[1,0]
	v_pk_mul_f32 v[96:97], v[96:97], v[182:183] op_sel_hi:[1,0]
	v_pk_mul_f32 v[94:95], v[94:95], v[182:183] op_sel_hi:[1,0]
	v_pk_mul_f32 v[92:93], v[92:93], v[182:183] op_sel_hi:[1,0]

; DI void nsa_ldsfrag(KVFrag& f, const unsigned char* slot, int qi, int quad) {
;     ...
;   for (int a = 0; a < 2; ++a) { const unsigned char* kp = slot + (krow + 4 * a) * NSA_KROW + quad * 16; f.k[a][0] = mk8(*(const u32x4*)kp); f.k[a][1] = mk8(*(const u32x4*)(kp + 64)); }
; #pragma unroll
;   for (int dt = 0; dt < 4; ++dt) f.v[dt] = mk8(*(const u32x4*)(slot + 32 * NSA_KROW + (dt * 16 + qi) * NSA_VROW + quad * 16));
; template <int MODE>
; DI void nsa_branch(const bf16_t* __restrict__ Kb, const bf16_t* __restrict__ Vtb, unsigned char* lds, int nb, int t, int cur, unsigned selmask, unsigned umall,
;                    const bf16x8 (&qf)[4][2], f32x4 (&O)[4][4], float (&m)[4], float (&l)[4], bool online) {
;     ...
;     *(u32x4*)(slot1 + ldst) = rb;
;     __syncthreads();
;     rb = *(const u32x4*)(gsrc + (long)kbof(min(n + 3, N - 1)) * gmul);
;     if (won) { KVFrag f; nsa_ldsfrag(f, slot1, qi, quad); nsa_chunk<MODE>(f, j * 64 + 32, t, bit, qf, O, m, l, quad, online); }
.LBB0_737:
	s_min_i32 s14, s54, s55
	s_lshr_b32 s14, s14, 1
	v_add_u32_e32 v116, 0x12600, v161
	s_waitcnt vmcnt(1)
	ds_write_b128 v116, v[108:111]
	s_waitcnt lgkmcnt(0)
	s_barrier
	ds_read_b128 v[136:139], v178
	ds_read_b128 v[140:143], v178 offset:64
	ds_read_b128 v[144:147], v178 offset:576
	ds_read_b128 v[132:135], v178 offset:640
	ds_read_b128 v[128:131], v179
	ds_read_b128 v[124:127], v179 offset:1280
	ds_read_b128 v[120:123], v179 offset:2560
	ds_read_b128 v[116:119], v179 offset:3840
	v_readlane_b32 s14, v216, s14
	s_andn2_b64 vcc, exec, s[0:1]
	s_lshl_b32 s14, s14, 6
	s_or_b32 s14, s14, 32
	s_ashr_i32 s15, s14, 31
	s_lshl_b64 s[14:15], s[14:15], 7
	v_lshl_add_u64 v[108:109], v[168:169], 0, s[14:15]
	global_load_dwordx4 v[108:111], v[108:109], off
	s_cbranch_vccnz .LBB0_726
	s_and_b64 vcc, exec, s[10:11]
	s_cbranch_vccz .Lmy_nf_s2
	v_readfirstlane_b32 s58, v181
	v_readfirstlane_b32 s59, v160
	s_lshl_b32 s58, s58, 6
	s_add_u32 s60, s58, 63
	s_cmp_le_i32 s60, s59
	s_cbranch_scc0 .Lmy_nf_s2
	v_mov_b32_e32 v226, 0xff800000
	v_cndmask_b32_e64 v218, v226, 0, s[12:13]
	v_cndmask_b32_e64 v219, v226, 0, s[12:13]
	v_cndmask_b32_e64 v220, v226, 0, s[12:13]
	v_cndmask_b32_e64 v221, v226, 0, s[12:13]
	s_branch .Lmy_full_s2
.Lmy_nf_s2:
	v_lshl_or_b32 v181, v181, 6, v174
	v_cmp_le_i32_e32 vcc, v181, v160
	s_and_b64 s[16:17], s[12:13], vcc
	v_cmp_lt_i32_e32 vcc, v181, v160
	v_or_b32_e32 v148, 2, v181
	s_and_b64 s[18:19], s[12:13], vcc
	v_cmp_le_i32_e32 vcc, v148, v160
	v_or_b32_e32 v148, 3, v181
	s_and_b64 s[44:45], s[12:13], vcc
	v_cmp_le_i32_e32 vcc, v148, v160
	v_or_b32_e32 v148, 4, v181
	s_and_b64 s[46:47], s[12:13], vcc
	v_cmp_le_i32_e32 vcc, v148, v160
	v_or_b32_e32 v152, 5, v181
	s_and_b64 s[14:15], s[12:13], vcc
	v_cmp_le_i32_e32 vcc, v152, v160
	v_or_b32_e32 v182, 6, v181
	s_and_b64 s[48:49], s[12:13], vcc
	v_cmp_le_i32_e32 vcc, v182, v160
	v_or_b32_e32 v181, 7, v181
	s_and_b64 s[50:51], s[12:13], vcc
	v_cmp_le_i32_e32 vcc, v181, v160
	s_and_b64 s[12:13], s[12:13], vcc
	s_and_b64 vcc, exec, s[10:11]
	v_mov_b32_e32 v226, 0xff800000
	v_cndmask_b32_e64 v218, v226, 0, s[16:17]
	v_cndmask_b32_e64 v219, v226, 0, s[18:19]
	v_cndmask_b32_e64 v220, v226, 0, s[44:45]
	v_cndmask_b32_e64 v221, v226, 0, s[46:47]
	v_cndmask_b32_e64 v222, v226, 0, s[14:15]
	v_cndmask_b32_e64 v223, v226, 0, s[48:49]
	v_cndmask_b32_e64 v224, v226, 0, s[50:51]
	v_cndmask_b32_e64 v225, v226, 0, s[12:13]
	s_nop 1
	s_cbranch_vccnz .Lmy_fast_s2
	s_waitcnt lgkmcnt(7)
	v_mfma_f32_16x16x32_bf16 v[148:151], v[136:139], v[8:11], v[218:221]
	s_waitcnt lgkmcnt(6)
	v_mfma_f32_16x16x32_bf16 v[152:155], v[140:143], v[12:15], v[148:151]
	s_waitcnt lgkmcnt(5)
	v_mfma_f32_16x16x32_bf16 v[148:151], v[144:147], v[8:11], v[222:225]
	s_waitcnt lgkmcnt(4)
	v_mfma_f32_16x16x32_bf16 v[148:151], v[132:135], v[12:15], v[148:151]
	s_nop 7
	s_cbranch_vccnz .LBB0_740
	v_mul_f32_e32 v181, 0x3e38aa3b, v152
	v_max_f32_e32 v181, 0xf149f2ca, v181
	v_cndmask_b32_e64 v181, v232, v181, s[16:17]
	v_mul_f32_e32 v182, 0x3e38aa3b, v153
	v_max_f32_e32 v182, v181, v182
	v_cndmask_b32_e64 v181, v181, v182, s[18:19]
	v_mul_f32_e32 v182, 0x3e38aa3b, v154
	v_max_f32_e32 v182, v181, v182
	v_cndmask_b32_e64 v181, v181, v182, s[44:45]
	v_mul_f32_e32 v182, 0x3e38aa3b, v155
	v_max_f32_e32 v182, v181, v182
	v_cndmask_b32_e64 v181, v181, v182, s[46:47]
	v_mul_f32_e32 v182, 0x3e38aa3b, v148
	v_max_f32_e32 v182, v181, v182
	v_cndmask_b32_e64 v181, v181, v182, s[14:15]
	v_mul_f32_e32 v182, 0x3e38aa3b, v149
	v_max_f32_e32 v183, v181, v181
	v_max_f32_e32 v182, v183, v182
	v_cndmask_b32_e64 v181, v181, v182, s[48:49]
	v_mul_f32_e32 v182, 0x3e38aa3b, v150
	v_max_f32_e32 v183, v181, v181
	v_max_f32_e32 v182, v183, v182
	v_cndmask_b32_e64 v181, v181, v182, s[50:51]
	v_mul_f32_e32 v182, 0x3e38aa3b, v151
	v_max_f32_e32 v183, v181, v181
	v_max_f32_e32 v182, v183, v182
	v_cndmask_b32_e64 v181, v181, v182, s[12:13]
	ds_bpermute_b32 v182, v175, v181
	v_max_f32_e32 v181, v181, v181
	s_waitcnt lgkmcnt(0)
	v_max_f32_e32 v182, v182, v182
	v_max_f32_e32 v181, v181, v182
	ds_bpermute_b32 v182, v159, v181
	s_waitcnt lgkmcnt(0)
	v_max3_f32 v181, v3, v181, v182
	v_sub_f32_e32 v3, v3, v181
	v_exp_f32_e32 v182, v3
	v_mov_b32_e32 v3, v181
	v_mul_f32_e32 v167, v167, v182
	v_pk_mul_f32 v[106:107], v[106:107], v[182:183] op_sel_hi:[1,0]
	v_pk_mul_f32 v[104:105], v[104:105], v[182:183] op_sel_hi:[1,0]
	v_pk_mul_f32 v[102:103], v[102:103], v[182:183] op_sel_hi:[1,0]
	v_pk_mul_f32 v[100:101], v[100:101], v[182:183] op_sel_hi:[1,0]
	v_pk_mul_f32 v[98:99], v[98:99], v[182:183] op_sel_hi:[1,0]
	v_pk_mul_f32 v[96:97], v[96:97], v[182:183] op_sel_hi:[1,0]
	v_pk_mul_f32 v[94:95], v[94:95], v[182:183] op_sel_hi:[1,0]
	v_pk_mul_f32 v[92:93], v[92:93], v[182:183] op_sel_hi:[1,0]

; DI int my_tid() { int t = threadIdx.x; asm volatile("" : "+v"(t)); return t; }
; template <int MODE>
; DI void nsa_branch(const bf16_t* __restrict__ Kb, const bf16_t* __restrict__ Vtb, unsigned char* lds, int nb, int t, int cur, unsigned selmask, unsigned umall,
;                    const bf16x8 (&qf)[4][2], f32x4 (&O)[4][4], float (&m)[4], float (&l)[4], bool online) {
;   const int tid = my_tid(), lane = tid & 63, qi = lane & 15, quad = lane >> 4;
;   const int* blist = (const int*)(lds + NSA_BLIST);
;   const bool isv = tid >= 256;
;   const int t2 = tid & 255;
;   const bf16_t* gsrc = isv ? Vtb + (t2 >> 2) * 32 + (t2 & 3) * 8 : Kb + (long)(t2 >> 3) * 64 + (t2 & 7) * 8;
;   const long gmul = 64;
;   const int ldst = isv ? 32 * NSA_KROW + (t2 >> 2) * NSA_VROW + (t2 & 3) * 16 : (t2 >> 3) * NSA_KROW + (t2 & 7) * 16;
;   unsigned char* slot0 = lds + NSA_SLOT0; unsigned char* slot1 = slot0 + NSA_SLOT;
;   const int N = 2 * nb;
;   auto kbof = [&](int n) { return blist[n >> 1] * 64 + (n & 1) * 32; };
;   u32x4 ra = *(const u32x4*)(gsrc + (long)kbof(0) * gmul), rb = *(const u32x4*)(gsrc + (long)kbof(1) * gmul);
;   *(u32x4*)(slot0 + ldst) = ra;
;   __syncthreads();
; DI void nsa_wave(const Params& p, int layer, int b, int g, int t0, unsigned char* lds, bf16_t* ybase) {
;     ...
;     const int cur0 = (t0 >> 7) * 2, jlo = cur0 >= 8 ? cur0 - 8 : 0;
;     nb = cur0 + 2 - jlo;
;     if (my_tid() < nb) blist[my_tid()] = jlo + my_tid();
;     __syncthreads();
;     nsa_branch<1>(p.kw() + (long)bg * SEQ * 64, p.vwt() + (long)bg * 64 * SEQ, lds, nb, t, cur, selmask, umall, qf, O, m, l, on_w);
.LBB0_749:
	s_or_b64 exec, exec, s[0:1]
	v_mov_b32_e32 v109, v210
	s_movk_i32 s0, 0xff
	s_waitcnt lgkmcnt(0)
	s_barrier
	v_lshlrev_b32_e32 v217, 2, v228
	v_add_u32_e32 v217, 0x14c20, v217
	ds_read_b32 v216, v217
	s_waitcnt lgkmcnt(0)
	s_nop 0
	v_cmp_lt_i32_e32 vcc, s0, v109
	s_movk_i32 s0, 0x100
	v_cmp_gt_i32_e64 s[0:1], s0, v109
	v_lshlrev_b32_e32 v3, 4, v109
	s_and_saveexec_b64 s[10:11], s[0:1]
	s_xor_b64 s[0:1], exec, s[10:11]
	v_mov_b32_e32 v0, 3
	v_lshrrev_b32_sdwa v0, v0, v109 dst_sel:DWORD dst_unused:UNUSED_PAD src0_sel:DWORD src1_sel:BYTE_0
	v_and_b32_e32 v2, 0x70, v3
	s_movk_i32 s4, 0x90
	v_mad_u32_u24 v2, v0, s4, v2
	s_andn2_saveexec_b64 s[0:1], s[0:1]
	v_mov_b32_e32 v0, 2
	v_lshrrev_b32_sdwa v0, v0, v109 dst_sel:DWORD dst_unused:UNUSED_PAD src0_sel:DWORD src1_sel:BYTE_0
	v_mul_u32_u24_e32 v0, 0x50, v0
	v_and_b32_e32 v2, 48, v3
	s_movk_i32 s4, 0x1200
	v_add3_u32 v2, v0, v2, s4
	s_or_b64 exec, exec, s[0:1]
	v_mov_b32_e32 v44, s30
	ds_read_b32 v44, v44
	v_cndmask_b32_e32 v0, v252, v229, vcc
	v_cndmask_b32_e32 v42, v235, v236, vcc
	v_lshl_add_u64 v[40:41], s[40:41], 0, v[0:1]
	s_lshl_b32 s36, s8, 1
	v_lshlrev_b32_sdwa v0, v238, v109 dst_sel:DWORD dst_unused:UNUSED_PAD src0_sel:DWORD src1_sel:BYTE_0
	s_waitcnt lgkmcnt(0)
	v_readfirstlane_b32 s0, v44
	v_lshl_add_u64 v[40:41], v[40:41], 0, s[36:37]
	v_cndmask_b32_e64 v43, v237, 48, vcc
	v_and_b32_e32 v0, v0, v42
	s_lshl_b32 s0, s0, 6
	v_lshl_add_u64 v[40:41], v[40:41], 0, v[0:1]
	v_and_b32_e32 v0, v3, v43
	s_ashr_i32 s1, s0, 31
	v_lshl_add_u64 v[164:165], v[40:41], 0, v[0:1]
	s_lshl_b64 s[8:9], s[0:1], 7
	s_or_b32 s0, s0, 32
	v_lshl_add_u64 v[40:41], v[164:165], 0, s[8:9]
	s_ashr_i32 s1, s0, 31
	global_load_dwordx4 v[40:43], v[40:41], off
	s_lshl_b64 s[0:1], s[0:1], 7
	v_lshl_add_u64 v[44:45], v[164:165], 0, s[0:1]
	global_load_dwordx4 v[104:107], v[44:45], off
	v_add_u32_e32 v161, 32, v2
	v_mov_b32_e32 v2, v1
	v_mov_b32_e32 v3, v1
	v_add_u32_e32 v166, 0x10000, v161
	v_mov_b32_e32 v155, 0
	v_mov_b32_e32 v0, v1
	v_mov_b64_e32 v[102:103], v[2:3]
	v_mov_b64_e32 v[98:99], v[2:3]
	v_mov_b64_e32 v[94:95], v[2:3]
	v_mov_b64_e32 v[90:91], v[2:3]
	v_mov_b64_e32 v[86:87], v[2:3]
	v_mov_b64_e32 v[82:83], v[2:3]
	v_mov_b64_e32 v[78:79], v[2:3]
	v_mov_b64_e32 v[74:75], v[2:3]
	v_mov_b64_e32 v[70:71], v[2:3]
	v_mov_b64_e32 v[66:67], v[2:3]
	v_mov_b64_e32 v[62:63], v[2:3]
	v_mov_b64_e32 v[58:59], v[2:3]
	v_mov_b64_e32 v[54:55], v[2:3]
	v_mov_b64_e32 v[50:51], v[2:3]
	v_mov_b64_e32 v[46:47], v[2:3]
	v_cmp_lt_i32_e32 vcc, 0, v108
	v_mov_b32_e32 v154, v155
	v_mov_b32_e32 v153, v155
	v_mov_b32_e32 v152, v155
	v_mov_b64_e32 v[100:101], v[0:1]
	v_mov_b64_e32 v[96:97], v[0:1]
	v_mov_b64_e32 v[92:93], v[0:1]
	v_mov_b64_e32 v[88:89], v[0:1]
	v_mov_b64_e32 v[84:85], v[0:1]
	v_mov_b64_e32 v[80:81], v[0:1]
	v_mov_b64_e32 v[76:77], v[0:1]
	v_mov_b64_e32 v[72:73], v[0:1]
	v_mov_b64_e32 v[68:69], v[0:1]
	v_mov_b64_e32 v[64:65], v[0:1]
	v_mov_b64_e32 v[60:61], v[0:1]
	v_mov_b64_e32 v[56:57], v[0:1]
	v_mov_b64_e32 v[52:53], v[0:1]
	v_mov_b64_e32 v[48:49], v[0:1]
	v_mov_b64_e32 v[44:45], v[0:1]
	s_waitcnt vmcnt(1)
	ds_write_b128 v166, v[40:43]
	v_mov_b64_e32 v[42:43], v[2:3]
	v_mov_b64_e32 v[40:41], v[0:1]
	s_waitcnt lgkmcnt(0)
	s_barrier
	s_and_saveexec_b64 s[42:43], vcc
	s_cbranch_execz .LBB0_705
	v_bfe_u32 v2, v109, 4, 2
	v_lshlrev_b32_e32 v3, 1, v109
	v_and_b32_e32 v40, 3, v109
	v_and_or_b32 v3, v3, 24, v40
	v_lshlrev_b32_e32 v40, 4, v2
	v_readlane_b32 s0, v254, 59
	v_and_b32_e32 v0, 15, v109
	v_cmp_lt_f32_e64 s[44:45], s25, v156
	v_add_u32_e32 v43, s0, v40
	v_readlane_b32 s0, v254, 60
	v_add_u32_e32 v41, s35, v40
	v_mul_u32_u24_e32 v42, 0x90, v3
	v_add_u32_e32 v45, s0, v40
	v_readlane_b32 s0, v254, 61
	v_mul_u32_u24_e32 v44, 0x50, v0
	v_lshlrev_b32_e32 v169, 3, v2
	v_add_u32_e32 v40, s0, v40
	v_mov_b32_e32 v2, v1
	v_mov_b32_e32 v3, v1
	v_lshlrev_b32_e32 v167, 1, v108
	v_cndmask_b32_e64 v179, v156, v232, s[44:45]
	v_mov_b32_e32 v0, v1
	v_mov_b32_e32 v152, 0
	v_add_u32_e32 v174, v41, v42
	v_add_u32_e32 v176, v43, v44
	v_add_u32_e32 v177, v45, v42
	v_add_u32_e32 v178, v40, v44
	v_mov_b64_e32 v[42:43], v[2:3]
	v_mov_b64_e32 v[46:47], v[2:3]
	v_mov_b64_e32 v[50:51], v[2:3]
	v_mov_b64_e32 v[54:55], v[2:3]
	v_mov_b64_e32 v[58:59], v[2:3]
	v_mov_b64_e32 v[62:63], v[2:3]
	v_mov_b64_e32 v[66:67], v[2:3]
	v_mov_b64_e32 v[70:71], v[2:3]
	v_mov_b64_e32 v[74:75], v[2:3]
	v_mov_b64_e32 v[78:79], v[2:3]
	v_mov_b64_e32 v[82:83], v[2:3]
	v_mov_b64_e32 v[86:87], v[2:3]
	v_mov_b64_e32 v[90:91], v[2:3]
	v_mov_b64_e32 v[94:95], v[2:3]
	v_mov_b64_e32 v[98:99], v[2:3]
	v_mov_b64_e32 v[102:103], v[2:3]
	v_add_u32_e32 v156, -8, v170
	v_add_u32_e32 v168, -2, v167
	s_mov_b32 s28, 3
	v_add_u32_e32 v171, 0xfffffe00, v160
	v_add_u32_e32 v172, -1, v167
	v_or_b32_e32 v173, 32, v169
	s_mov_b64 s[52:53], 0
	v_mov_b64_e32 v[40:41], v[0:1]
	v_mov_b64_e32 v[44:45], v[0:1]
	v_mov_b64_e32 v[48:49], v[0:1]
	v_mov_b64_e32 v[52:53], v[0:1]
	v_mov_b64_e32 v[56:57], v[0:1]
	v_mov_b64_e32 v[60:61], v[0:1]
	v_mov_b64_e32 v[64:65], v[0:1]
	v_mov_b64_e32 v[68:69], v[0:1]
	v_mov_b64_e32 v[72:73], v[0:1]
	v_mov_b64_e32 v[76:77], v[0:1]
	v_mov_b64_e32 v[80:81], v[0:1]
	v_mov_b64_e32 v[84:85], v[0:1]
	v_mov_b64_e32 v[88:89], v[0:1]
	v_mov_b64_e32 v[92:93], v[0:1]
	v_mov_b64_e32 v[96:97], v[0:1]
	v_mov_b64_e32 v[100:101], v[0:1]
	v_mov_b32_e32 v0, v179
	v_mov_b32_e32 v2, v179
	v_mov_b32_e32 v3, v179
	v_mov_b32_e32 v153, v152
	v_mov_b32_e32 v154, v152
	v_mov_b32_e32 v155, v152
	s_branch .LBB0_757

; DI void nsa_ldsfrag(KVFrag& f, const unsigned char* slot, int qi, int quad) {
;     ...
;   for (int a = 0; a < 2; ++a) { const unsigned char* kp = slot + (krow + 4 * a) * NSA_KROW + quad * 16; f.k[a][0] = mk8(*(const u32x4*)kp); f.k[a][1] = mk8(*(const u32x4*)(kp + 64)); }
; #pragma unroll
;   for (int dt = 0; dt < 4; ++dt) f.v[dt] = mk8(*(const u32x4*)(slot + 32 * NSA_KROW + (dt * 16 + qi) * NSA_VROW + quad * 16));
; template <int MODE>
; DI void nsa_branch(const bf16_t* __restrict__ Kb, const bf16_t* __restrict__ Vtb, unsigned char* lds, int nb, int t, int cur, unsigned selmask, unsigned umall,
;                    const bf16x8 (&qf)[4][2], f32x4 (&O)[4][4], float (&m)[4], float (&l)[4], bool online) {
;     ...
;   auto kbof = [&](int n) { return blist[n >> 1] * 64 + (n & 1) * 32; };
;   u32x4 ra = *(const u32x4*)(gsrc + (long)kbof(0) * gmul), rb = *(const u32x4*)(gsrc + (long)kbof(1) * gmul);
;     ...
;   for (int n = 0; n < N; n += 2) {
;     const int j = blist[n >> 1];
;     const bool won = MODE == 0 ? ((umall >> j) & 1u) != 0 : (j >= cur - 8 && j <= cur);
;     const bool bit = (selmask >> j) & 1u;
;     ra = *(const u32x4*)(gsrc + (long)kbof(min(n + 2, N - 2)) * gmul);
;     if (won) { KVFrag f; nsa_ldsfrag(f, slot0, qi, quad); nsa_chunk<MODE>(f, j * 64, t, bit, qf, O, m, l, quad, online); }
.LBB0_757:
	ds_read_b128 v[132:135], v174
	ds_read_b128 v[136:139], v174 offset:64
	ds_read_b128 v[140:143], v174 offset:576
	ds_read_b128 v[128:131], v174 offset:640
	ds_read_b128 v[124:127], v176
	ds_read_b128 v[120:123], v176 offset:1280
	ds_read_b128 v[116:119], v176 offset:2560
	s_add_i32 s36, s28, -1
	s_sub_u32 s58, s30, 0x14c20
	s_lshr_b32 s58, s58, 2
	v_readlane_b32 s58, v216, s58
	v_readfirstlane_b32 s59, v168
	s_min_i32 s59, s36, s59
	s_lshr_b32 s59, s59, 1
	v_readlane_b32 s59, v216, s59
	s_nop 1
	v_mov_b32_e32 v180, s58
	v_mov_b32_e32 v108, s59
	v_cmp_ge_i32_e32 vcc, v180, v156
	v_cmp_le_i32_e64 s[0:1], v180, v170
	v_cndmask_b32_e64 v112, 0, 1, s[44:45]
	s_and_b64 s[54:55], vcc, s[0:1]
	v_lshlrev_b32_e32 v108, 6, v108
	v_ashrrev_i32_e32 v109, 31, v108
	v_lshlrev_b64 v[108:109], 7, v[108:109]
	v_lshl_add_u64 v[108:109], v[164:165], 0, v[108:109]
	global_load_dwordx4 v[108:111], v[108:109], off
	v_cmp_ne_u32_e64 s[8:9], 1, v112
	s_and_saveexec_b64 s[56:57], s[54:55]
	s_cbranch_execz .LBB0_767
	s_and_b64 vcc, exec, s[8:9]
	s_cbranch_vccz .Lmy_nf_w1
	v_readfirstlane_b32 s58, v180
	v_readfirstlane_b32 s59, v160
	s_lshl_b32 s58, s58, 6
	s_add_u32 s60, s58, 63
	s_cmp_le_i32 s60, s59
	s_cbranch_scc0 .Lmy_nf_w1
	s_sub_u32 s60, s59, 0x1f1
	s_cmp_gt_i32 s58, s60
	s_cbranch_scc0 .Lmy_nf_w1
	ds_read_b128 v[112:115], v176 offset:3840
	s_branch .Lmy_full_w1
.Lmy_nf_w1:
	v_lshl_or_b32 v181, v180, 6, v169
	v_cmp_le_i32_e32 vcc, v181, v160
	v_cmp_gt_i32_e64 s[0:1], v181, v171
	s_and_b64 s[10:11], vcc, s[0:1]
	v_cmp_lt_i32_e32 vcc, v181, v160
	v_cmp_ge_i32_e64 s[0:1], v181, v171
	v_or_b32_e32 v144, 2, v181
	s_and_b64 s[14:15], vcc, s[0:1]
	v_cmp_le_i32_e32 vcc, v144, v160
	v_cmp_gt_i32_e64 s[0:1], v144, v171
	v_or_b32_e32 v144, 3, v181
	s_and_b64 s[18:19], vcc, s[0:1]
	v_cmp_le_i32_e32 vcc, v144, v160
	v_cmp_gt_i32_e64 s[0:1], v144, v171
	v_or_b32_e32 v144, 4, v181
	s_and_b64 s[46:47], vcc, s[0:1]
	v_cmp_le_i32_e32 vcc, v144, v160
	v_cmp_gt_i32_e64 s[0:1], v144, v171
	v_or_b32_e32 v144, 5, v181
	ds_read_b128 v[112:115], v176 offset:3840
	s_and_b64 s[12:13], vcc, s[0:1]
	v_cmp_le_i32_e32 vcc, v144, v160
	v_cmp_gt_i32_e64 s[0:1], v144, v171
	v_or_b32_e32 v148, 6, v181
	s_and_b64 s[16:17], vcc, s[0:1]
	v_cmp_le_i32_e32 vcc, v148, v160
	v_cmp_gt_i32_e64 s[0:1], v148, v171
	v_or_b32_e32 v181, 7, v181
	s_and_b64 s[48:49], vcc, s[0:1]
	v_cmp_le_i32_e32 vcc, v181, v160
	v_cmp_gt_i32_e64 s[0:1], v181, v171
	s_and_b64 s[50:51], vcc, s[0:1]
	s_and_b64 vcc, exec, s[8:9]
	v_mov_b32_e32 v226, 0xff800000
	v_cndmask_b32_e64 v218, v226, 0, s[10:11]
	v_cndmask_b32_e64 v219, v226, 0, s[14:15]
	v_cndmask_b32_e64 v220, v226, 0, s[18:19]
	v_cndmask_b32_e64 v221, v226, 0, s[46:47]
	v_cndmask_b32_e64 v222, v226, 0, s[12:13]
	v_cndmask_b32_e64 v223, v226, 0, s[16:17]
	v_cndmask_b32_e64 v224, v226, 0, s[48:49]
	v_cndmask_b32_e64 v225, v226, 0, s[50:51]
	s_nop 1
	s_cbranch_vccnz .Lmy_fast_w1
	s_waitcnt lgkmcnt(7)
	v_mfma_f32_16x16x32_bf16 v[144:147], v[132:135], v[8:11], v[218:221]
	s_waitcnt lgkmcnt(6)
	v_mfma_f32_16x16x32_bf16 v[148:151], v[136:139], v[12:15], v[144:147]
	s_waitcnt lgkmcnt(5)
	v_mfma_f32_16x16x32_bf16 v[144:147], v[140:143], v[8:11], v[222:225]
	s_waitcnt lgkmcnt(4)
	v_mfma_f32_16x16x32_bf16 v[144:147], v[128:131], v[12:15], v[144:147]
	s_nop 7
	s_cbranch_vccnz .LBB0_760
	v_mul_f32_e32 v181, 0x3e38aa3b, v148
	v_max_f32_e32 v181, 0xf149f2ca, v181
	v_cndmask_b32_e64 v181, v232, v181, s[10:11]
	v_mul_f32_e32 v182, 0x3e38aa3b, v149
	v_max_f32_e32 v182, v181, v182
	v_cndmask_b32_e64 v181, v181, v182, s[14:15]
	v_mul_f32_e32 v182, 0x3e38aa3b, v150
	v_max_f32_e32 v182, v181, v182
	v_cndmask_b32_e64 v181, v181, v182, s[18:19]
	v_mul_f32_e32 v182, 0x3e38aa3b, v151
	v_max_f32_e32 v182, v181, v182
	v_cndmask_b32_e64 v181, v181, v182, s[46:47]
	v_mul_f32_e32 v182, 0x3e38aa3b, v144
	v_max_f32_e32 v182, v181, v182
	v_cndmask_b32_e64 v181, v181, v182, s[12:13]
	v_mul_f32_e32 v182, 0x3e38aa3b, v145
	v_max_f32_e32 v183, v181, v181
	v_max_f32_e32 v182, v183, v182
	v_cndmask_b32_e64 v181, v181, v182, s[16:17]
	v_mul_f32_e32 v182, 0x3e38aa3b, v146
	v_max_f32_e32 v183, v181, v181
	v_max_f32_e32 v182, v183, v182
	v_cndmask_b32_e64 v181, v181, v182, s[48:49]
	v_mul_f32_e32 v182, 0x3e38aa3b, v147
	v_max_f32_e32 v183, v181, v181
	v_max_f32_e32 v182, v183, v182
	v_cndmask_b32_e64 v181, v181, v182, s[50:51]
	ds_bpermute_b32 v182, v175, v181
	v_max_f32_e32 v181, v181, v181
	s_waitcnt lgkmcnt(0)
	v_max_f32_e32 v182, v182, v182
	v_max_f32_e32 v181, v181, v182
	ds_bpermute_b32 v182, v159, v181
	s_waitcnt lgkmcnt(0)
	v_max3_f32 v181, v3, v181, v182
	v_sub_f32_e32 v3, v3, v181
	v_exp_f32_e32 v182, v3
	v_mov_b32_e32 v3, v181
	v_mul_f32_e32 v155, v155, v182
	v_pk_mul_f32 v[102:103], v[102:103], v[182:183] op_sel_hi:[1,0]
	v_pk_mul_f32 v[100:101], v[100:101], v[182:183] op_sel_hi:[1,0]
	v_pk_mul_f32 v[98:99], v[98:99], v[182:183] op_sel_hi:[1,0]
	v_pk_mul_f32 v[96:97], v[96:97], v[182:183] op_sel_hi:[1,0]
	v_pk_mul_f32 v[94:95], v[94:95], v[182:183] op_sel_hi:[1,0]
	v_pk_mul_f32 v[92:93], v[92:93], v[182:183] op_sel_hi:[1,0]
	v_pk_mul_f32 v[90:91], v[90:91], v[182:183] op_sel_hi:[1,0]
	v_pk_mul_f32 v[88:89], v[88:89], v[182:183] op_sel_hi:[1,0]

; DI void nsa_ldsfrag(KVFrag& f, const unsigned char* slot, int qi, int quad) {
;     ...
;   for (int a = 0; a < 2; ++a) { const unsigned char* kp = slot + (krow + 4 * a) * NSA_KROW + quad * 16; f.k[a][0] = mk8(*(const u32x4*)kp); f.k[a][1] = mk8(*(const u32x4*)(kp + 64)); }
; #pragma unroll
;   for (int dt = 0; dt < 4; ++dt) f.v[dt] = mk8(*(const u32x4*)(slot + 32 * NSA_KROW + (dt * 16 + qi) * NSA_VROW + quad * 16));
; template <int MODE>
; DI void nsa_branch(const bf16_t* __restrict__ Kb, const bf16_t* __restrict__ Vtb, unsigned char* lds, int nb, int t, int cur, unsigned selmask, unsigned umall,
;                    const bf16x8 (&qf)[4][2], f32x4 (&O)[4][4], float (&m)[4], float (&l)[4], bool online) {
;     ...
;     *(u32x4*)(slot1 + ldst) = rb;
;     __syncthreads();
;     rb = *(const u32x4*)(gsrc + (long)kbof(min(n + 3, N - 1)) * gmul);
;     if (won) { KVFrag f; nsa_ldsfrag(f, slot1, qi, quad); nsa_chunk<MODE>(f, j * 64 + 32, t, bit, qf, O, m, l, quad, online); }
;     *(u32x4*)(slot0 + ldst) = ra;
.LBB0_767:
	s_or_b64 exec, exec, s[56:57]
	v_add_u32_e32 v112, 0x12600, v161
	s_waitcnt vmcnt(1)
	ds_write_b128 v112, v[104:107]
	v_min_i32_e32 v104, s28, v172
	v_lshlrev_b32_e32 v104, 1, v104
	v_and_b32_e32 v104, -4, v104
	v_add_u32_e32 v104, 32, v104
	v_add_u32_e32 v104, 0x14c00, v104
	s_waitcnt lgkmcnt(0)
	s_barrier
	ds_read_b128 v[132:135], v177
	ds_read_b128 v[136:139], v177 offset:64
	ds_read_b128 v[140:143], v177 offset:576
	ds_read_b128 v[128:131], v177 offset:640
	ds_read_b128 v[124:127], v178
	ds_read_b128 v[120:123], v178 offset:1280
	ds_read_b128 v[116:119], v178 offset:2560
	ds_read_b128 v[112:115], v178 offset:3840
	v_readfirstlane_b32 s58, v172
	s_min_i32 s58, s28, s58
	s_lshr_b32 s58, s58, 1
	v_readlane_b32 s58, v216, s58
	s_nop 1
	v_mov_b32_e32 v104, s58
	v_lshl_or_b32 v104, v104, 6, 32
	v_ashrrev_i32_e32 v105, 31, v104
	v_lshlrev_b64 v[104:105], 7, v[104:105]
	v_lshl_add_u64 v[104:105], v[164:165], 0, v[104:105]
	global_load_dwordx4 v[104:107], v[104:105], off
	s_and_saveexec_b64 s[56:57], s[54:55]
	s_cbranch_execz .LBB0_756
	s_and_b64 vcc, exec, s[8:9]
	s_cbranch_vccz .Lmy_nf_w2
	v_readfirstlane_b32 s58, v180
	v_readfirstlane_b32 s59, v160
	s_lshl_b32 s58, s58, 6
	s_add_u32 s60, s58, 63
	s_cmp_le_i32 s60, s59
	s_cbranch_scc0 .Lmy_nf_w2
	s_sub_u32 s60, s59, 0x1f1
	s_cmp_gt_i32 s58, s60
	s_cbranch_scc0 .Lmy_nf_w2
	s_branch .Lmy_full_w2
.Lmy_nf_w2:
	v_lshl_or_b32 v180, v180, 6, v173
	v_cmp_le_i32_e32 vcc, v180, v160
	v_cmp_gt_i32_e64 s[0:1], v180, v171
	s_and_b64 s[10:11], vcc, s[0:1]
	v_cmp_lt_i32_e32 vcc, v180, v160
	v_cmp_ge_i32_e64 s[0:1], v180, v171
	v_or_b32_e32 v144, 2, v180
	s_and_b64 s[14:15], vcc, s[0:1]
	v_cmp_le_i32_e32 vcc, v144, v160
	v_cmp_gt_i32_e64 s[0:1], v144, v171
	v_or_b32_e32 v144, 3, v180
	s_and_b64 s[18:19], vcc, s[0:1]
	v_cmp_le_i32_e32 vcc, v144, v160
	v_cmp_gt_i32_e64 s[0:1], v144, v171
	v_or_b32_e32 v144, 4, v180
	s_and_b64 s[46:47], vcc, s[0:1]
	v_cmp_le_i32_e32 vcc, v144, v160
	v_cmp_gt_i32_e64 s[0:1], v144, v171
	v_or_b32_e32 v144, 5, v180
	s_and_b64 s[12:13], vcc, s[0:1]
	v_cmp_le_i32_e32 vcc, v144, v160
	v_cmp_gt_i32_e64 s[0:1], v144, v171
	v_or_b32_e32 v148, 6, v180
	s_and_b64 s[16:17], vcc, s[0:1]
	v_cmp_le_i32_e32 vcc, v148, v160
	v_cmp_gt_i32_e64 s[0:1], v148, v171
	v_or_b32_e32 v180, 7, v180
	s_and_b64 s[48:49], vcc, s[0:1]
	v_cmp_le_i32_e32 vcc, v180, v160
	v_cmp_gt_i32_e64 s[0:1], v180, v171
	s_and_b64 s[50:51], vcc, s[0:1]
	s_and_b64 vcc, exec, s[8:9]
	v_mov_b32_e32 v226, 0xff800000
	v_cndmask_b32_e64 v218, v226, 0, s[10:11]
	v_cndmask_b32_e64 v219, v226, 0, s[14:15]
	v_cndmask_b32_e64 v220, v226, 0, s[18:19]
	v_cndmask_b32_e64 v221, v226, 0, s[46:47]
	v_cndmask_b32_e64 v222, v226, 0, s[12:13]
	v_cndmask_b32_e64 v223, v226, 0, s[16:17]
	v_cndmask_b32_e64 v224, v226, 0, s[48:49]
	v_cndmask_b32_e64 v225, v226, 0, s[50:51]
	s_nop 1
	s_cbranch_vccnz .Lmy_fast_w2
	s_waitcnt lgkmcnt(7)
	v_mfma_f32_16x16x32_bf16 v[144:147], v[132:135], v[8:11], v[218:221]
	s_waitcnt lgkmcnt(6)
	v_mfma_f32_16x16x32_bf16 v[148:151], v[136:139], v[12:15], v[144:147]
	s_waitcnt lgkmcnt(5)
	v_mfma_f32_16x16x32_bf16 v[144:147], v[140:143], v[8:11], v[222:225]
	s_waitcnt lgkmcnt(4)
	v_mfma_f32_16x16x32_bf16 v[144:147], v[128:131], v[12:15], v[144:147]
	s_nop 7
	s_cbranch_vccnz .LBB0_770
	v_mul_f32_e32 v180, 0x3e38aa3b, v148
	v_max_f32_e32 v180, 0xf149f2ca, v180
	v_cndmask_b32_e64 v180, v232, v180, s[10:11]
	v_mul_f32_e32 v181, 0x3e38aa3b, v149
	v_max_f32_e32 v181, v180, v181
	v_cndmask_b32_e64 v180, v180, v181, s[14:15]
	v_mul_f32_e32 v181, 0x3e38aa3b, v150
	v_max_f32_e32 v181, v180, v181
	v_cndmask_b32_e64 v180, v180, v181, s[18:19]
	v_mul_f32_e32 v181, 0x3e38aa3b, v151
	v_max_f32_e32 v181, v180, v181
	v_cndmask_b32_e64 v180, v180, v181, s[46:47]
	v_mul_f32_e32 v181, 0x3e38aa3b, v144
	v_max_f32_e32 v181, v180, v181
	v_cndmask_b32_e64 v180, v180, v181, s[12:13]
	v_mul_f32_e32 v181, 0x3e38aa3b, v145
	v_max_f32_e32 v182, v180, v180
	v_max_f32_e32 v181, v182, v181
	v_cndmask_b32_e64 v180, v180, v181, s[16:17]
	v_mul_f32_e32 v181, 0x3e38aa3b, v146
	v_max_f32_e32 v182, v180, v180
	v_max_f32_e32 v181, v182, v181
	v_cndmask_b32_e64 v180, v180, v181, s[48:49]
	v_mul_f32_e32 v181, 0x3e38aa3b, v147
	v_max_f32_e32 v182, v180, v180
	v_max_f32_e32 v181, v182, v181
	v_cndmask_b32_e64 v180, v180, v181, s[50:51]
	ds_bpermute_b32 v181, v175, v180
	v_max_f32_e32 v180, v180, v180
	s_waitcnt lgkmcnt(0)
	v_max_f32_e32 v181, v181, v181
	v_max_f32_e32 v180, v180, v181
	ds_bpermute_b32 v181, v159, v180
	s_waitcnt lgkmcnt(0)
	v_max3_f32 v181, v3, v180, v181
	v_sub_f32_e32 v3, v3, v181
	v_exp_f32_e32 v180, v3
	v_mov_b32_e32 v3, v181
	v_mul_f32_e32 v155, v155, v180
	v_pk_mul_f32 v[102:103], v[102:103], v[180:181] op_sel_hi:[1,0]
	v_pk_mul_f32 v[100:101], v[100:101], v[180:181] op_sel_hi:[1,0]
	v_pk_mul_f32 v[98:99], v[98:99], v[180:181] op_sel_hi:[1,0]
	v_pk_mul_f32 v[96:97], v[96:97], v[180:181] op_sel_hi:[1,0]
	v_pk_mul_f32 v[94:95], v[94:95], v[180:181] op_sel_hi:[1,0]
	v_pk_mul_f32 v[92:93], v[92:93], v[180:181] op_sel_hi:[1,0]
	v_pk_mul_f32 v[90:91], v[90:91], v[180:181] op_sel_hi:[1,0]
	v_pk_mul_f32 v[88:89], v[88:89], v[180:181] op_sel_hi:[1,0]
